# full-line (8 rows x 128B) LDS-DMA pieces + new LDS swizzle in P4 K-loop, on top of ssq hoist and G1 quota
# baseline (speedup 1.0000x reference)
; #define PG8_STAGE(bufoff, gbase, voff) do { _Pragma("unroll") for (int _i = 0; _i < 2; ++_i) \
;         __builtin_amdgcn_global_load_lds((const unsigned*)((const char*)(gbase) + (voff)[_i]), (PG8_LAS unsigned*)(lds + (bufoff) + ldsw + _i * 8192), 16, 0, 0); } while (0)
; #define PG8_WAIT_V(n) asm volatile("s_waitcnt vmcnt(" #n ")" ::: "memory")
; #define PG8_BAR __builtin_amdgcn_s_barrier()
; template <class Epi, class Sched, bool ALIGN_EPI = false, bool SP2 = false>
; __device__ __forceinline__ void gemm_phase(PG8_LAS unsigned char* lds, const Gemm g, const Sched& S, const Epi& E) {
;     ...
;     for (int i = 0; i < 2; ++i) { int R, C; stage_rc(tid * 16 + i * 8192, R, C); const int Rb = Epi::PERM ? ((R & ~31) + perm32(R & 31)) : R;
;         voffA[i] = (unsigned)(R * K + C) * 2u; voffB[i] = (unsigned)(Rb * K + C) * 2u; }
;     const size_t kstep = (size_t)(BK * 2);
;     const size_t hstep = (size_t)HALF * K * 2;
;     const size_t tstep = 2 * hstep;
;     const unsigned ldsw = (unsigned)wid * 1024u;
;     const int aoff = lds_byte(wr * 64 + fr, fq * 8), boff = lds_byte(wc * 32 + fr, fq * 8);
;     ...
;         PG8_STAGE(PG8_SB(0, 0), cB, voffB); PG8_STAGE(PG8_SB(0, 1), cB + hstep, voffB); PG8_STAGE(PG8_SA(0, 0), cA, voffA); PG8_STAGE(PG8_SA(0, 1), cA + hstep, voffA);
;         if (wr == 1) PG8_BAR;
;         PG8_WAIT_V(2); PG8_BAR;
;         PG8_STAGE(PG8_SB(1, 0), cB + kstep, voffB); PG8_STAGE(PG8_SA(1, 0), cA + kstep, voffA); PG8_STAGE(PG8_SB(1, 1), cB + hstep + kstep, voffB);
;         PG8_WAIT_V(6); PG8_BAR;
.LBB0_1043:
	s_andn2_b64 vcc, exec, s[2:3]
	s_cbranch_vccnz .LBB0_1058
	v_readlane_b32 s2, v248, 27
	v_mov_b32_e32 v3, v204
	v_readlane_b32 s3, v248, 28
	s_andn2_b64 vcc, exec, s[2:3]
	v_readfirstlane_b32 s2, v3
	s_cbranch_vccnz .LBB0_1058
	v_lshlrev_b32_e32 v1, 4, v3
	v_add_u32_e32 v0, 0x2000, v1
	v_ashrrev_i32_e32 v4, 31, v0
	v_lshrrev_b32_e32 v4, 22, v4
	v_add_u32_e32 v4, v0, v4
	v_ashrrev_i32_e32 v8, 10, v4
	v_mul_i32_i24_e32 v4, 0x400, v8
	v_sub_u32_e32 v0, v0, v4
	v_lshrrev_b32_e32 v4, 4, v0
	v_bitop3_b32 v0, v4, v0, 32 bitop3:0x6c
	v_ashrrev_i32_e32 v4, 31, v0
	v_lshrrev_b32_e32 v4, 26, v4
	v_add_u32_e32 v4, v0, v4
	v_lshlrev_b32_e32 v5, 3, v8
	v_ashrrev_i32_e32 v9, 6, v4
	v_and_b32_e32 v5, -16, v5
	v_add_u32_e32 v5, v9, v5
	v_and_b32_e32 v6, 3, v9
	s_mov_b32 s6, 0xfffe0
	v_lshrrev_b32_e32 v7, 2, v5
	v_lshlrev_b32_e32 v10, 1, v5
	v_and_b32_e32 v4, 0xc0, v4
	v_and_or_b32 v6, v5, s6, v6
	v_and_b32_e32 v7, 4, v7
	v_and_b32_e32 v10, 24, v10
	v_sub_u32_e32 v0, v0, v4
	v_or3_b32 v6, v6, v7, v10
	v_lshlrev_b32_e32 v7, 5, v8
	v_ashrrev_i16_sdwa v0, v207, sext(v0) dst_sel:DWORD dst_unused:UNUSED_PAD src0_sel:DWORD src1_sel:BYTE_0
	v_and_b32_e32 v7, 32, v7
	v_bfe_i32 v10, v0, 0, 16
	v_add_lshl_u32 v4, v7, v10, 1
	v_lshl_add_u32 v0, v6, 12, v4
	v_lshl_add_u32 v132, v5, 12, v4
	v_bfe_i32 v4, v3, 27, 1
	v_lshrrev_b32_e32 v4, 22, v4
	v_add_u32_e32 v4, v1, v4
	v_and_b32_e32 v4, 0xfffffc00, v4
	v_sub_u32_e32 v1, v1, v4
	v_lshrrev_b32_e32 v4, 4, v1
	v_ashrrev_i32_e32 v5, 31, v3
	v_bitop3_b32 v1, v4, v1, 32 bitop3:0x6c
	v_lshrrev_b32_e32 v5, 26, v5
	v_ashrrev_i32_e32 v4, 31, v1
	v_add_u32_e32 v5, v3, v5
	v_lshrrev_b32_e32 v4, 26, v4
	v_ashrrev_i32_e32 v12, 6, v5
	v_add_u32_e32 v4, v1, v4
	v_lshlrev_b32_e32 v5, 3, v12
	v_ashrrev_i32_e32 v11, 6, v4
	v_and_b32_e32 v5, -16, v5
	v_add_u32_e32 v5, v11, v5
	v_and_b32_e32 v6, 3, v11
	v_lshrrev_b32_e32 v7, 2, v5
	v_lshlrev_b32_e32 v13, 1, v5
	v_and_b32_e32 v4, 0xc0, v4
	s_ashr_i32 s3, s2, 6
	v_and_or_b32 v6, v5, s6, v6
	v_and_b32_e32 v7, 4, v7
	v_and_b32_e32 v13, 24, v13
	v_sub_u32_e32 v1, v1, v4
	s_ashr_i32 s10, s2, 8
	s_lshl_b32 s42, s3, 10
	v_or3_b32 v6, v6, v7, v13
	v_lshlrev_b32_e32 v7, 5, v12
	v_ashrrev_i16_sdwa v1, v207, sext(v1) dst_sel:DWORD dst_unused:UNUSED_PAD src0_sel:DWORD src1_sel:BYTE_0
	v_readlane_b32 s6, v248, 31
	v_and_b32_e32 v7, 32, v7
	v_bfe_i32 v13, v1, 0, 16
	v_readlane_b32 s7, v248, 32
	s_add_u32 s6, s46, s6
	v_add_lshl_u32 v1, v7, v13, 1
	s_addc_u32 s7, s47, s7
	s_add_i32 s43, s42, 0
	v_lshl_add_u32 v134, v6, 12, v1
	s_add_i32 m0, s43, 0x10000
	v_lshl_add_u32 v136, v5, 12, v1
	v_lshrrev_b32_e32 v240, 3, v3
	v_bfe_u32 v241, v3, 4, 3
	v_and_b32_e32 v242, 7, v3
	v_xor_b32_e32 v242, v242, v241
	v_lshlrev_b32_e32 v242, 4, v242
	v_bfe_u32 v243, v3, 5, 2
	v_lshlrev_b32_e32 v243, 3, v243
	v_bfe_u32 v244, v3, 7, 1
	v_lshlrev_b32_e32 v244, 2, v244
	v_bfe_u32 v245, v3, 3, 2
	v_or3_b32 v243, v243, v244, v245
	v_and_b32_e32 v246, 32, v240
	v_or_b32_e32 v243, v243, v246
	v_lshl_add_u32 v136, v240, 12, v242
	v_lshl_add_u32 v134, v243, 12, v242
	v_add_u32_e32 v132, 0x40000, v136
	v_add_u32_e32 v0, 0x40000, v134
	global_load_lds_dwordx4 v134, s[6:7]
	s_add_i32 m0, s43, 0x12000
	s_add_u32 s8, s6, 0x80000
	global_load_lds_dwordx4 v0, s[6:7]
	s_addc_u32 s9, s7, 0
	s_add_i32 m0, s43, 0x14000
	s_add_i32 s44, s43, 0x2000
	global_load_lds_dwordx4 v134, s[8:9]
	s_add_i32 m0, s43, 0x16000
	s_add_i32 s45, s43, 0x4000
	global_load_lds_dwordx4 v0, s[8:9]
	s_mov_b32 m0, s43
	v_readlane_b32 s8, v250, 57
	global_load_lds_dwordx4 v136, s[0:1]
	s_mov_b32 m0, s44
	v_readlane_b32 s9, v250, 58
	global_load_lds_dwordx4 v132, s[0:1]
	s_mov_b32 m0, s45
	s_add_i32 s48, s43, 0x6000
	v_mov_b32_e32 v135, v2
	s_nop 0
	global_load_lds_dwordx4 v136, s[8:9]
	s_mov_b32 m0, s48
	v_mov_b32_e32 v1, v2
	global_load_lds_dwordx4 v132, s[8:9]
	s_cmp_eq_u32 s10, 1
	v_lshl_add_u64 v[4:5], s[6:7], 0, v[134:135]
	s_cselect_b64 s[8:9], -1, 0
	s_cmp_lg_u32 s10, 1
	v_lshl_add_u64 v[6:7], s[6:7], 0, v[0:1]
	s_cbranch_scc1 .LBB0_1047
	s_barrier
.LBB0_1047:
	v_lshrrev_b32_e32 v20, 1, v3
	v_and_b32_e32 v20, 24, v20
	v_and_b32_e32 v18, 15, v3
	v_lshlrev_b32_e32 v21, 1, v20
	v_lshlrev_b32_e32 v3, 2, v3
	s_lshl_b32 s3, s3, 5
	v_mov_b32_e32 v137, v2
	v_lshl_or_b32 v19, s10, 6, v18
	v_lshl_or_b32 v18, v18, 6, v21
	s_lshl_b32 s10, s10, 13
	v_and_b32_e32 v3, 32, v3
	s_and_b32 s3, s3, 0x60
	s_add_i32 m0, s43, 0x18000
	v_lshl_add_u64 v[4:5], v[4:5], 0, s[28:29]
	v_lshl_add_u64 v[14:15], s[0:1], 0, v[136:137]
	v_mov_b32_e32 v133, v2
	v_bitop3_b32 v21, v18, s10, v3 bitop3:0xde
	s_lshl_b32 s10, s3, 7
	s_waitcnt vmcnt(2)
	s_barrier
	global_load_lds_dwordx4 v[4:5], off
	v_lshl_add_u64 v[4:5], v[6:7], 0, s[28:29]
	s_add_i32 m0, s43, 0x1a000
	s_add_i32 s49, s43, 0x8000
	s_add_i32 s50, s43, 0xa000
	v_lshl_add_u64 v[16:17], s[0:1], 0, v[132:133]
	v_bitop3_b32 v3, v18, s10, v3 bitop3:0xde
	global_load_lds_dwordx4 v[4:5], off
	v_lshl_add_u64 v[4:5], v[14:15], 0, s[28:29]
	s_mov_b32 m0, s49
	s_add_u32 s10, s6, 0x80080
	global_load_lds_dwordx4 v[4:5], off
	v_lshl_add_u64 v[4:5], v[16:17], 0, s[28:29]
	s_mov_b32 m0, s50
	s_addc_u32 s11, s7, 0
	global_load_lds_dwordx4 v[4:5], off
	s_add_i32 m0, s43, 0x1c000
	v_lshl_add_u64 v[4:5], s[10:11], 0, v[134:135]
	global_load_lds_dwordx4 v[4:5], off
	v_lshl_add_u64 v[4:5], s[10:11], 0, v[0:1]
	s_add_i32 m0, s43, 0x1e000
	s_cmpk_lt_u32 s2, 0x100
	global_load_lds_dwordx4 v[4:5], off
	v_lshlrev_b32_e32 v4, 15, v12
	v_and_b32_e32 v4, 0xffff0000, v4
	v_readlane_b32 s2, v250, 59
	v_lshl_add_u32 v4, v11, 12, v4
	v_and_b32_e32 v5, 1, v12
	v_add_u32_e32 v148, s2, v19
	v_or_b32_e32 v149, s3, v20
	v_lshl_or_b32 v4, v5, 6, v4
	v_readlane_b32 s2, v247, 10
	v_lshl_add_u32 v4, v13, 1, v4
	v_mov_b32_e32 v5, v2
	v_readlane_b32 s3, v247, 11
	s_waitcnt vmcnt(6)
	s_cselect_b64 s[10:11], -1, 0
	s_mov_b32 s51, 0
	v_lshl_add_u64 v[138:139], s[2:3], 0, v[4:5]
	v_lshlrev_b32_e32 v4, 15, v8
	v_and_b32_e32 v4, 0xffff0000, v4
	v_lshl_add_u32 v4, v9, 12, v4
	v_and_b32_e32 v5, 1, v8
	v_lshl_or_b32 v4, v5, 6, v4
	v_lshl_add_u32 v4, v10, 1, v4
	v_mov_b32_e32 v5, v2
	v_lshl_add_u64 v[140:141], s[2:3], 0, v[4:5]
	v_add_u32_e32 v150, 0, v21
	v_lshl_add_u64 v[138:139], s[2:3], 0, v[136:137]
	v_lshl_add_u64 v[140:141], s[2:3], 0, v[132:133]
	v_bfe_u32 v240, v204, 1, 3
	v_bfe_u32 v241, v204, 4, 2
	v_xor_b32_e32 v240, v240, v241
	v_lshlrev_b32_e32 v240, 4, v240
	v_and_b32_e32 v241, 7, v204
	v_lshl_add_u32 v240, v241, 7, v240
	v_bfe_u32 v241, v204, 3, 1
	v_bfe_u32 v242, v204, 8, 1
	v_lshl_add_u32 v242, v242, 3, v241
	v_lshl_add_u32 v150, v242, 10, v240
	v_xor_b32_e32 v251, 64, v150
	v_bfe_u32 v242, v204, 6, 2
	v_lshl_add_u32 v242, v242, 2, v241
	v_lshl_add_u32 v3, v242, 10, v240
	v_xor_b32_e32 v252, 64, v3
	v_readlane_b32 s12, v248, 29
	s_barrier
	v_readlane_b32 s13, v248, 30
	s_branch .LBB0_1050

; #define PG8_STAGE(bufoff, gbase, voff) do { _Pragma("unroll") for (int _i = 0; _i < 2; ++_i) \
;         __builtin_amdgcn_global_load_lds((const unsigned*)((const char*)(gbase) + (voff)[_i]), (PG8_LAS unsigned*)(lds + (bufoff) + ldsw + _i * 8192), 16, 0, 0); } while (0)
; #define PG8_LDA(dst, b, h) do { _Pragma("unroll") for (int m = 0; m < 4; ++m) _Pragma("unroll") for (int k = 0; k < 2; ++k) dst[m][k] = *(const PG8_LAS bf16x8*)(lds + PG8_SA(b, h) + aoff + m * 2048 + k * 1024); } while (0)
; #define PG8_LDB(dst, b, h) do { _Pragma("unroll") for (int n = 0; n < 2; ++n) _Pragma("unroll") for (int k = 0; k < 2; ++k) dst[n][k] = *(const PG8_LAS bf16x8*)(lds + PG8_SB(b, h) + boff + n * 2048 + k * 1024); } while (0)
; #define PG8_MMA(ai, bj, At, Bt) do { __builtin_amdgcn_s_setprio(1); _Pragma("unroll") for (int m = 0; m < 4; ++m) _Pragma("unroll") for (int n = 0; n < 2; ++n) _Pragma("unroll") for (int k = 0; k < 2; ++k) \
;         acc[ai][bj][m][n] = __builtin_amdgcn_mfma_f32_16x16x32_bf16(Bt[n][k], At[m][k], acc[ai][bj][m][n], 0, 0, 0); __builtin_amdgcn_s_setprio(0); } while (0)
; #define PG8_WAIT_V(n) asm volatile("s_waitcnt vmcnt(" #n ")" ::: "memory")
; #define PG8_WAIT_L(n) asm volatile("s_waitcnt lgkmcnt(" #n ")" ::: "memory")
; #define PG8_BAR __builtin_amdgcn_s_barrier()
; #define PG8_SCHED __builtin_amdgcn_sched_barrier(0)
; template <class Epi, class Sched, bool ALIGN_EPI = false, bool SP2 = false>
; __device__ __forceinline__ void gemm_phase(PG8_LAS unsigned char* lds, const Gemm g, const Sched& S, const Epi& E) {
;     ...
;             PG8_LDB(B0, 0, 0); PG8_LDB(B1, 0, 1); PG8_SCHED; PG8_LDA(At, 0, 0); PG8_STAGE(PG8_SA(1, 1), a1 + hstep, voffA);
;             PG8_WAIT_V(8); PG8_WAIT_L(0); PG8_BAR; PG8_MMA(0, 0, At, B0); PG8_MMA(0, 1, At, B1); PG8_BAR; PG8_SCHED;
;             PG8_LDA(At, 0, 1); PG8_STAGE(PG8_SB(0, 0), b2, voffB); PG8_STAGE(PG8_SB(0, 1), b2 + hstep, voffB); PG8_STAGE(PG8_SA(0, 0), a2, voffA);
;             PG8_WAIT_V(8); PG8_WAIT_L(0); PG8_BAR; PG8_MMA(1, 0, At, B0); PG8_MMA(1, 1, At, B1); PG8_BAR; PG8_SCHED;
.LBB0_1051:
	s_add_u32 s36, s31, s2
	s_addc_u32 s37, s91, s3
	s_add_u32 s36, s36, 0x16200100
	s_addc_u32 s37, s37, 0
	s_add_u32 s57, s54, s2
	s_addc_u32 s58, s55, s3
	s_add_i32 s59, 0, 0x10000
	s_cmpk_eq_i32 s2, 0xf00
	s_cselect_b32 s41, s1, s37
	s_cselect_b32 s40, s0, s36
	v_add_u32_e32 v146, s59, v3
	v_add_u32_e32 v253, s59, v252
	s_cselect_b32 s37, s13, s58
	s_cselect_b32 s36, s53, s57
	s_add_i32 s57, 0, 0x14000
	ds_read_b128 v[142:145], v146
	ds_read_b128 v[152:155], v253
	ds_read_b128 v[156:159], v146 offset:2048
	ds_read_b128 v[172:175], v253 offset:2048
	v_add_u32_e32 v146, s57, v3
	v_add_u32_e32 v253, s57, v252
	ds_read_b128 v[176:179], v146
	ds_read_b128 v[180:183], v253
	ds_read_b128 v[184:187], v146 offset:2048
	ds_read_b128 v[188:191], v253 offset:2048
	v_lshl_add_u64 v[146:147], v[138:139], 0, s[2:3]
	s_add_i32 m0, s43, 0xc000
	ds_read_b128 v[192:195], v150
	ds_read_b128 v[196:199], v251
	ds_read_b128 v[200:203], v150 offset:2048
	ds_read_b128 v[212:215], v251 offset:2048
	ds_read_b128 v[216:219], v150 offset:4096
	ds_read_b128 v[220:223], v251 offset:4096
	ds_read_b128 v[224:227], v150 offset:6144
	ds_read_b128 v[228:231], v251 offset:6144
	global_load_lds_dwordx4 v[146:147], off
	v_lshl_add_u64 v[146:147], v[140:141], 0, s[2:3]
	s_add_i32 m0, s43, 0xe000
	s_nop 0
	global_load_lds_dwordx4 v[146:147], off
	s_waitcnt vmcnt(8)
	s_waitcnt lgkmcnt(0)
	s_barrier
	s_setprio 1
	s_waitcnt lgkmcnt(0)
	v_mfma_f32_16x16x32_bf16 v[120:123], v[142:145], v[192:195], v[120:123]
	v_mfma_f32_16x16x32_bf16 v[116:119], v[156:159], v[192:195], v[116:119]
	v_mfma_f32_16x16x32_bf16 v[104:107], v[142:145], v[200:203], v[104:107]
	v_mfma_f32_16x16x32_bf16 v[100:103], v[156:159], v[200:203], v[100:103]
	v_mfma_f32_16x16x32_bf16 v[88:91], v[142:145], v[216:219], v[88:91]
	v_mfma_f32_16x16x32_bf16 v[84:87], v[156:159], v[216:219], v[84:87]
	v_mfma_f32_16x16x32_bf16 v[72:75], v[142:145], v[224:227], v[72:75]
	v_mfma_f32_16x16x32_bf16 v[68:71], v[156:159], v[224:227], v[68:71]
	v_mfma_f32_16x16x32_bf16 v[120:123], v[152:155], v[196:199], v[120:123]
	v_mfma_f32_16x16x32_bf16 v[116:119], v[172:175], v[196:199], v[116:119]
	v_mfma_f32_16x16x32_bf16 v[104:107], v[152:155], v[212:215], v[104:107]
	v_mfma_f32_16x16x32_bf16 v[100:103], v[172:175], v[212:215], v[100:103]
	v_mfma_f32_16x16x32_bf16 v[88:91], v[152:155], v[220:223], v[88:91]
	v_mfma_f32_16x16x32_bf16 v[84:87], v[172:175], v[220:223], v[84:87]
	v_mfma_f32_16x16x32_bf16 v[72:75], v[152:155], v[228:231], v[72:75]
	v_mfma_f32_16x16x32_bf16 v[68:71], v[172:175], v[228:231], v[68:71]
	s_setprio 0
	s_setprio 1
	v_mfma_f32_16x16x32_bf16 v[128:131], v[176:179], v[192:195], v[128:131]
	v_mfma_f32_16x16x32_bf16 v[124:127], v[184:187], v[192:195], v[124:127]
	v_mfma_f32_16x16x32_bf16 v[112:115], v[176:179], v[200:203], v[112:115]
	v_mfma_f32_16x16x32_bf16 v[108:111], v[184:187], v[200:203], v[108:111]
	v_mfma_f32_16x16x32_bf16 v[96:99], v[176:179], v[216:219], v[96:99]
	v_mfma_f32_16x16x32_bf16 v[92:95], v[184:187], v[216:219], v[92:95]
	v_mfma_f32_16x16x32_bf16 v[80:83], v[176:179], v[224:227], v[80:83]
	v_mfma_f32_16x16x32_bf16 v[76:79], v[184:187], v[224:227], v[76:79]
	v_mfma_f32_16x16x32_bf16 v[128:131], v[180:183], v[196:199], v[128:131]
	v_mfma_f32_16x16x32_bf16 v[124:127], v[188:191], v[196:199], v[124:127]
	v_mfma_f32_16x16x32_bf16 v[112:115], v[180:183], v[212:215], v[112:115]
	v_mfma_f32_16x16x32_bf16 v[108:111], v[188:191], v[212:215], v[108:111]
	v_mfma_f32_16x16x32_bf16 v[96:99], v[180:183], v[220:223], v[96:99]
	v_mfma_f32_16x16x32_bf16 v[92:95], v[188:191], v[220:223], v[92:95]
	v_mfma_f32_16x16x32_bf16 v[80:83], v[180:183], v[228:231], v[80:83]
	v_mfma_f32_16x16x32_bf16 v[76:79], v[188:191], v[228:231], v[76:79]
	s_setprio 0
	s_barrier
	s_add_i32 s58, s59, s42
	v_lshl_add_u64 v[146:147], s[36:37], 0, v[134:135]
	s_mov_b32 m0, s58
	ds_read_b128 v[192:195], v150 offset:16384
	ds_read_b128 v[196:199], v251 offset:16384
	ds_read_b128 v[200:203], v150 offset:18432
	ds_read_b128 v[212:215], v251 offset:18432
	ds_read_b128 v[216:219], v150 offset:20480
	ds_read_b128 v[220:223], v251 offset:20480
	ds_read_b128 v[224:227], v150 offset:22528
	ds_read_b128 v[228:231], v251 offset:22528
	global_load_lds_dwordx4 v[146:147], off
	s_add_i32 m0, s58, 0x2000
	s_add_u32 s58, s36, 0x80000
	v_lshl_add_u64 v[232:233], s[36:37], 0, v[0:1]
	s_addc_u32 s59, s37, 0
	s_add_i32 s57, s57, s42
	global_load_lds_dwordx4 v[232:233], off
	v_lshl_add_u64 v[234:235], s[58:59], 0, v[134:135]
	s_mov_b32 m0, s57
	v_lshl_add_u64 v[236:237], s[40:41], 0, v[132:133]
	global_load_lds_dwordx4 v[234:235], off
	v_lshl_add_u64 v[234:235], s[58:59], 0, v[0:1]
	s_add_i32 m0, s57, 0x2000
	s_nop 0
	global_load_lds_dwordx4 v[234:235], off
	v_lshl_add_u64 v[234:235], s[40:41], 0, v[136:137]
	s_mov_b32 m0, s43
	s_nop 0
	global_load_lds_dwordx4 v[234:235], off
	s_mov_b32 m0, s44
	s_nop 0
	global_load_lds_dwordx4 v[236:237], off
	s_waitcnt vmcnt(8)
	s_waitcnt lgkmcnt(0)
	s_barrier
; #define PG8_STAGE(bufoff, gbase, voff) do { _Pragma("unroll") for (int _i = 0; _i < 2; ++_i) \
;         __builtin_amdgcn_global_load_lds((const unsigned*)((const char*)(gbase) + (voff)[_i]), (PG8_LAS unsigned*)(lds + (bufoff) + ldsw + _i * 8192), 16, 0, 0); } while (0)
; #define PG8_LDA(dst, b, h) do { _Pragma("unroll") for (int m = 0; m < 4; ++m) _Pragma("unroll") for (int k = 0; k < 2; ++k) dst[m][k] = *(const PG8_LAS bf16x8*)(lds + PG8_SA(b, h) + aoff + m * 2048 + k * 1024); } while (0)
; #define PG8_LDB(dst, b, h) do { _Pragma("unroll") for (int n = 0; n < 2; ++n) _Pragma("unroll") for (int k = 0; k < 2; ++k) dst[n][k] = *(const PG8_LAS bf16x8*)(lds + PG8_SB(b, h) + boff + n * 2048 + k * 1024); } while (0)
; #define PG8_MMA(ai, bj, At, Bt) do { __builtin_amdgcn_s_setprio(1); _Pragma("unroll") for (int m = 0; m < 4; ++m) _Pragma("unroll") for (int n = 0; n < 2; ++n) _Pragma("unroll") for (int k = 0; k < 2; ++k) \
;         acc[ai][bj][m][n] = __builtin_amdgcn_mfma_f32_16x16x32_bf16(Bt[n][k], At[m][k], acc[ai][bj][m][n], 0, 0, 0); __builtin_amdgcn_s_setprio(0); } while (0)
; #define PG8_WAIT_V(n) asm volatile("s_waitcnt vmcnt(" #n ")" ::: "memory")
; #define PG8_WAIT_L(n) asm volatile("s_waitcnt lgkmcnt(" #n ")" ::: "memory")
; #define PG8_BAR __builtin_amdgcn_s_barrier()
; #define PG8_SCHED __builtin_amdgcn_sched_barrier(0)
; template <class Epi, class Sched, bool ALIGN_EPI = false, bool SP2 = false>
; __device__ __forceinline__ void gemm_phase(PG8_LAS unsigned char* lds, const Gemm g, const Sched& S, const Epi& E) {
;     ...
;             PG8_WAIT_V(8); PG8_WAIT_L(0); PG8_BAR; PG8_MMA(1, 0, At, B0); PG8_MMA(1, 1, At, B1); PG8_BAR; PG8_SCHED;
;             PG8_LDB(B0, 1, 0); PG8_LDB(B1, 1, 1); PG8_SCHED; PG8_LDA(At, 1, 0); PG8_STAGE(PG8_SA(0, 1), a2 + hstep, voffA);
;             PG8_WAIT_V(8); PG8_WAIT_L(0); PG8_BAR; PG8_MMA(0, 0, At, B0); PG8_MMA(0, 1, At, B1); PG8_BAR; PG8_SCHED;
	s_setprio 1
	s_waitcnt lgkmcnt(0)
	v_mfma_f32_16x16x32_bf16 v[56:59], v[142:145], v[192:195], v[56:59]
	v_mfma_f32_16x16x32_bf16 v[52:55], v[156:159], v[192:195], v[52:55]
	v_mfma_f32_16x16x32_bf16 v[40:43], v[142:145], v[200:203], v[40:43]
	v_mfma_f32_16x16x32_bf16 v[36:39], v[156:159], v[200:203], v[36:39]
	v_mfma_f32_16x16x32_bf16 v[24:27], v[142:145], v[216:219], v[24:27]
	v_mfma_f32_16x16x32_bf16 v[20:23], v[156:159], v[216:219], v[20:23]
	v_mfma_f32_16x16x32_bf16 v[8:11], v[142:145], v[224:227], v[8:11]
	v_mfma_f32_16x16x32_bf16 v[4:7], v[156:159], v[224:227], v[4:7]
	v_mfma_f32_16x16x32_bf16 v[56:59], v[152:155], v[196:199], v[56:59]
	v_mfma_f32_16x16x32_bf16 v[52:55], v[172:175], v[196:199], v[52:55]
	v_mfma_f32_16x16x32_bf16 v[40:43], v[152:155], v[212:215], v[40:43]
	v_mfma_f32_16x16x32_bf16 v[36:39], v[172:175], v[212:215], v[36:39]
	v_mfma_f32_16x16x32_bf16 v[24:27], v[152:155], v[220:223], v[24:27]
	v_mfma_f32_16x16x32_bf16 v[20:23], v[172:175], v[220:223], v[20:23]
	v_mfma_f32_16x16x32_bf16 v[8:11], v[152:155], v[228:231], v[8:11]
	v_mfma_f32_16x16x32_bf16 v[4:7], v[172:175], v[228:231], v[4:7]
	s_setprio 0
	s_setprio 1
	v_mfma_f32_16x16x32_bf16 v[64:67], v[176:179], v[192:195], v[64:67]
	v_mfma_f32_16x16x32_bf16 v[60:63], v[184:187], v[192:195], v[60:63]
	v_mfma_f32_16x16x32_bf16 v[48:51], v[176:179], v[200:203], v[48:51]
	v_mfma_f32_16x16x32_bf16 v[44:47], v[184:187], v[200:203], v[44:47]
	v_mfma_f32_16x16x32_bf16 v[32:35], v[176:179], v[216:219], v[32:35]
	v_mfma_f32_16x16x32_bf16 v[28:31], v[184:187], v[216:219], v[28:31]
	v_mfma_f32_16x16x32_bf16 v[16:19], v[176:179], v[224:227], v[16:19]
	v_mfma_f32_16x16x32_bf16 v[12:15], v[184:187], v[224:227], v[12:15]
	v_mfma_f32_16x16x32_bf16 v[64:67], v[180:183], v[196:199], v[64:67]
	v_mfma_f32_16x16x32_bf16 v[60:63], v[188:191], v[196:199], v[60:63]
	v_mfma_f32_16x16x32_bf16 v[48:51], v[180:183], v[212:215], v[48:51]
	v_mfma_f32_16x16x32_bf16 v[44:47], v[188:191], v[212:215], v[44:47]
	v_mfma_f32_16x16x32_bf16 v[32:35], v[180:183], v[220:223], v[32:35]
	v_mfma_f32_16x16x32_bf16 v[28:31], v[188:191], v[220:223], v[28:31]
	v_mfma_f32_16x16x32_bf16 v[16:19], v[180:183], v[228:231], v[16:19]
	v_mfma_f32_16x16x32_bf16 v[12:15], v[188:191], v[228:231], v[12:15]
	s_setprio 0
	s_barrier
	s_add_i32 s57, 0, 0x18000
	v_add_u32_e32 v151, s57, v3
	v_add_u32_e32 v253, s57, v252
	s_add_i32 s58, 0, 0x1c000
	ds_read_b128 v[142:145], v151
	ds_read_b128 v[152:155], v253
	ds_read_b128 v[156:159], v151 offset:2048
	ds_read_b128 v[172:175], v253 offset:2048
	v_add_u32_e32 v151, s58, v3
	v_add_u32_e32 v253, s58, v252
	ds_read_b128 v[176:179], v151
	ds_read_b128 v[180:183], v253
	ds_read_b128 v[184:187], v151 offset:2048
	ds_read_b128 v[188:191], v253 offset:2048
	s_add_u32 s40, s40, 0x80000
	s_addc_u32 s41, s41, 0
	s_mov_b32 m0, s45
	v_lshl_add_u64 v[238:239], s[40:41], 0, v[136:137]
	ds_read_b128 v[192:195], v150 offset:32768
	ds_read_b128 v[196:199], v251 offset:32768
	ds_read_b128 v[200:203], v150 offset:34816
	ds_read_b128 v[212:215], v251 offset:34816
	ds_read_b128 v[216:219], v150 offset:36864
	ds_read_b128 v[220:223], v251 offset:36864
	ds_read_b128 v[224:227], v150 offset:38912
	ds_read_b128 v[228:231], v251 offset:38912
	global_load_lds_dwordx4 v[238:239], off
	v_lshl_add_u64 v[238:239], s[40:41], 0, v[132:133]
	s_mov_b32 m0, s48
	s_nop 0
	global_load_lds_dwordx4 v[238:239], off
	s_waitcnt vmcnt(8)
	s_waitcnt lgkmcnt(0)
	s_barrier
	s_setprio 1
	s_waitcnt lgkmcnt(0)
	v_mfma_f32_16x16x32_bf16 v[120:123], v[142:145], v[192:195], v[120:123]
	v_mfma_f32_16x16x32_bf16 v[116:119], v[156:159], v[192:195], v[116:119]
	v_mfma_f32_16x16x32_bf16 v[104:107], v[142:145], v[200:203], v[104:107]
	v_mfma_f32_16x16x32_bf16 v[100:103], v[156:159], v[200:203], v[100:103]
	v_mfma_f32_16x16x32_bf16 v[88:91], v[142:145], v[216:219], v[88:91]
	v_mfma_f32_16x16x32_bf16 v[84:87], v[156:159], v[216:219], v[84:87]
	v_mfma_f32_16x16x32_bf16 v[72:75], v[142:145], v[224:227], v[72:75]
	v_mfma_f32_16x16x32_bf16 v[68:71], v[156:159], v[224:227], v[68:71]
	v_mfma_f32_16x16x32_bf16 v[120:123], v[152:155], v[196:199], v[120:123]
	v_mfma_f32_16x16x32_bf16 v[116:119], v[172:175], v[196:199], v[116:119]
	v_mfma_f32_16x16x32_bf16 v[104:107], v[152:155], v[212:215], v[104:107]
	v_mfma_f32_16x16x32_bf16 v[100:103], v[172:175], v[212:215], v[100:103]
	v_mfma_f32_16x16x32_bf16 v[88:91], v[152:155], v[220:223], v[88:91]
	v_mfma_f32_16x16x32_bf16 v[84:87], v[172:175], v[220:223], v[84:87]
	v_mfma_f32_16x16x32_bf16 v[72:75], v[152:155], v[228:231], v[72:75]
	v_mfma_f32_16x16x32_bf16 v[68:71], v[172:175], v[228:231], v[68:71]
	s_setprio 0
	s_setprio 1
	v_mfma_f32_16x16x32_bf16 v[128:131], v[176:179], v[192:195], v[128:131]
	v_mfma_f32_16x16x32_bf16 v[124:127], v[184:187], v[192:195], v[124:127]
	v_mfma_f32_16x16x32_bf16 v[112:115], v[176:179], v[200:203], v[112:115]
	v_mfma_f32_16x16x32_bf16 v[108:111], v[184:187], v[200:203], v[108:111]
	v_mfma_f32_16x16x32_bf16 v[96:99], v[176:179], v[216:219], v[96:99]
	v_mfma_f32_16x16x32_bf16 v[92:95], v[184:187], v[216:219], v[92:95]
	v_mfma_f32_16x16x32_bf16 v[80:83], v[176:179], v[224:227], v[80:83]
	v_mfma_f32_16x16x32_bf16 v[76:79], v[184:187], v[224:227], v[76:79]
	v_mfma_f32_16x16x32_bf16 v[128:131], v[180:183], v[196:199], v[128:131]
	v_mfma_f32_16x16x32_bf16 v[124:127], v[188:191], v[196:199], v[124:127]
	v_mfma_f32_16x16x32_bf16 v[112:115], v[180:183], v[212:215], v[112:115]
	v_mfma_f32_16x16x32_bf16 v[108:111], v[188:191], v[212:215], v[108:111]
	v_mfma_f32_16x16x32_bf16 v[96:99], v[180:183], v[220:223], v[96:99]
	v_mfma_f32_16x16x32_bf16 v[92:95], v[188:191], v[220:223], v[92:95]
	v_mfma_f32_16x16x32_bf16 v[80:83], v[180:183], v[228:231], v[80:83]
	v_mfma_f32_16x16x32_bf16 v[76:79], v[188:191], v[228:231], v[76:79]
	s_setprio 0
	s_barrier
; #define PG8_STAGE(bufoff, gbase, voff) do { _Pragma("unroll") for (int _i = 0; _i < 2; ++_i) \
;         __builtin_amdgcn_global_load_lds((const unsigned*)((const char*)(gbase) + (voff)[_i]), (PG8_LAS unsigned*)(lds + (bufoff) + ldsw + _i * 8192), 16, 0, 0); } while (0)
; #define PG8_LDA(dst, b, h) do { _Pragma("unroll") for (int m = 0; m < 4; ++m) _Pragma("unroll") for (int k = 0; k < 2; ++k) dst[m][k] = *(const PG8_LAS bf16x8*)(lds + PG8_SA(b, h) + aoff + m * 2048 + k * 1024); } while (0)
; #define PG8_MMA(ai, bj, At, Bt) do { __builtin_amdgcn_s_setprio(1); _Pragma("unroll") for (int m = 0; m < 4; ++m) _Pragma("unroll") for (int n = 0; n < 2; ++n) _Pragma("unroll") for (int k = 0; k < 2; ++k) \
;         acc[ai][bj][m][n] = __builtin_amdgcn_mfma_f32_16x16x32_bf16(Bt[n][k], At[m][k], acc[ai][bj][m][n], 0, 0, 0); __builtin_amdgcn_s_setprio(0); } while (0)
; #define PG8_WAIT_V(n) asm volatile("s_waitcnt vmcnt(" #n ")" ::: "memory")
; #define PG8_WAIT_L(n) asm volatile("s_waitcnt lgkmcnt(" #n ")" ::: "memory")
; #define PG8_BAR __builtin_amdgcn_s_barrier()
; #define PG8_SCHED __builtin_amdgcn_sched_barrier(0)
; template <class Epi, class Sched, bool ALIGN_EPI = false, bool SP2 = false>
; __device__ __forceinline__ void gemm_phase(PG8_LAS unsigned char* lds, const Gemm g, const Sched& S, const Epi& E) {
;     ...
;         for (int t = 0; t < nt; t += 2) {
;             const bool last = (t == nt - 2);
;     ...
;             PG8_LDA(At, 1, 1); PG8_STAGE(PG8_SB(1, 0), b3, voffB); PG8_STAGE(PG8_SB(1, 1), b3 + hstep, voffB); PG8_STAGE(PG8_SA(1, 0), a3, voffA);
;             PG8_WAIT_V(8); PG8_WAIT_L(0); PG8_BAR; PG8_MMA(1, 0, At, B0); PG8_MMA(1, 1, At, B1); PG8_BAR; PG8_SCHED;
	s_add_i32 s40, s57, s42
	v_lshl_add_u64 v[146:147], v[146:147], 0, s[28:29]
	s_mov_b32 m0, s40
	ds_read_b128 v[192:195], v150 offset:49152
	ds_read_b128 v[196:199], v251 offset:49152
	ds_read_b128 v[200:203], v150 offset:51200
	ds_read_b128 v[212:215], v251 offset:51200
	ds_read_b128 v[216:219], v150 offset:53248
	ds_read_b128 v[220:223], v251 offset:53248
	ds_read_b128 v[224:227], v150 offset:55296
	ds_read_b128 v[228:231], v251 offset:55296
	global_load_lds_dwordx4 v[146:147], off
	s_add_i32 m0, s40, 0x2000
	s_add_u32 s36, s36, 0x80080
	v_lshl_add_u64 v[146:147], v[232:233], 0, s[28:29]
	s_addc_u32 s37, s37, 0
	s_add_i32 s40, s58, s42
	global_load_lds_dwordx4 v[146:147], off
	v_lshl_add_u64 v[146:147], s[36:37], 0, v[134:135]
	s_mov_b32 m0, s40
	s_nop 0
	global_load_lds_dwordx4 v[146:147], off
	v_lshl_add_u64 v[146:147], s[36:37], 0, v[0:1]
	s_add_i32 m0, s40, 0x2000
	s_nop 0
	global_load_lds_dwordx4 v[146:147], off
	v_lshl_add_u64 v[146:147], v[234:235], 0, s[28:29]
	s_mov_b32 m0, s49
	s_nop 0
	global_load_lds_dwordx4 v[146:147], off
	v_lshl_add_u64 v[146:147], v[236:237], 0, s[28:29]
	s_mov_b32 m0, s50
	s_nop 0
	global_load_lds_dwordx4 v[146:147], off
	s_waitcnt vmcnt(8)
	s_waitcnt lgkmcnt(0)
	s_barrier
	s_setprio 1
	s_waitcnt lgkmcnt(0)
	v_mfma_f32_16x16x32_bf16 v[56:59], v[142:145], v[192:195], v[56:59]
	v_mfma_f32_16x16x32_bf16 v[52:55], v[156:159], v[192:195], v[52:55]
	v_mfma_f32_16x16x32_bf16 v[40:43], v[142:145], v[200:203], v[40:43]
	v_mfma_f32_16x16x32_bf16 v[36:39], v[156:159], v[200:203], v[36:39]
	v_mfma_f32_16x16x32_bf16 v[24:27], v[142:145], v[216:219], v[24:27]
	v_mfma_f32_16x16x32_bf16 v[20:23], v[156:159], v[216:219], v[20:23]
	v_mfma_f32_16x16x32_bf16 v[8:11], v[142:145], v[224:227], v[8:11]
	v_mfma_f32_16x16x32_bf16 v[4:7], v[156:159], v[224:227], v[4:7]
	v_mfma_f32_16x16x32_bf16 v[56:59], v[152:155], v[196:199], v[56:59]
	v_mfma_f32_16x16x32_bf16 v[52:55], v[172:175], v[196:199], v[52:55]
	v_mfma_f32_16x16x32_bf16 v[40:43], v[152:155], v[212:215], v[40:43]
	v_mfma_f32_16x16x32_bf16 v[36:39], v[172:175], v[212:215], v[36:39]
	v_mfma_f32_16x16x32_bf16 v[24:27], v[152:155], v[220:223], v[24:27]
	v_mfma_f32_16x16x32_bf16 v[20:23], v[172:175], v[220:223], v[20:23]
	v_mfma_f32_16x16x32_bf16 v[8:11], v[152:155], v[228:231], v[8:11]
	v_mfma_f32_16x16x32_bf16 v[4:7], v[172:175], v[228:231], v[4:7]
	s_setprio 0
	s_setprio 1
	v_mfma_f32_16x16x32_bf16 v[64:67], v[176:179], v[192:195], v[64:67]
	v_mfma_f32_16x16x32_bf16 v[60:63], v[184:187], v[192:195], v[60:63]
	v_mfma_f32_16x16x32_bf16 v[48:51], v[176:179], v[200:203], v[48:51]
	v_mfma_f32_16x16x32_bf16 v[44:47], v[184:187], v[200:203], v[44:47]
	v_mfma_f32_16x16x32_bf16 v[32:35], v[176:179], v[216:219], v[32:35]
	v_mfma_f32_16x16x32_bf16 v[28:31], v[184:187], v[216:219], v[28:31]
	v_mfma_f32_16x16x32_bf16 v[16:19], v[176:179], v[224:227], v[16:19]
	v_mfma_f32_16x16x32_bf16 v[12:15], v[184:187], v[224:227], v[12:15]
	v_mfma_f32_16x16x32_bf16 v[64:67], v[180:183], v[196:199], v[64:67]
	v_mfma_f32_16x16x32_bf16 v[60:63], v[188:191], v[196:199], v[60:63]
	v_mfma_f32_16x16x32_bf16 v[48:51], v[180:183], v[212:215], v[48:51]
	v_mfma_f32_16x16x32_bf16 v[44:47], v[188:191], v[212:215], v[44:47]
	v_mfma_f32_16x16x32_bf16 v[32:35], v[180:183], v[220:223], v[32:35]
	v_mfma_f32_16x16x32_bf16 v[28:31], v[188:191], v[220:223], v[28:31]
	v_mfma_f32_16x16x32_bf16 v[16:19], v[180:183], v[228:231], v[16:19]
	v_mfma_f32_16x16x32_bf16 v[12:15], v[188:191], v[228:231], v[12:15]
	s_setprio 0
	s_barrier
	s_add_i32 s56, s56, 2
	s_add_u32 s2, s2, 0x100
	s_addc_u32 s3, s3, 0
	s_cmp_gt_u32 s56, 29
	s_cbranch_scc0 .LBB0_1051
	s_and_b64 vcc, exec, s[10:11]
	s_cbranch_vccz .LBB0_1054
	s_barrier

; __global__ void __launch_bounds__(NWAVES * 64, 2) fwd_kernel(Args A) {
	.amdhsa_kernel _Z10fwd_kernel4Args
		.amdhsa_group_segment_fixed_size 0
		.amdhsa_private_segment_fixed_size 0
		.amdhsa_kernarg_size 416
		.amdhsa_user_sgpr_count 2
		.amdhsa_user_sgpr_dispatch_ptr 0
		.amdhsa_user_sgpr_queue_ptr 0
		.amdhsa_user_sgpr_kernarg_segment_ptr 1
		.amdhsa_user_sgpr_dispatch_id 0
		.amdhsa_user_sgpr_kernarg_preload_length 0
		.amdhsa_user_sgpr_kernarg_preload_offset 0
		.amdhsa_user_sgpr_private_segment_size 0
		.amdhsa_uses_dynamic_stack 0
		.amdhsa_enable_private_segment 0
		.amdhsa_system_sgpr_workgroup_id_x 1
		.amdhsa_system_sgpr_workgroup_id_y 0
		.amdhsa_system_sgpr_workgroup_id_z 0
		.amdhsa_system_sgpr_workgroup_info 0
		.amdhsa_system_vgpr_workitem_id 2
		.amdhsa_next_free_vgpr 254
		.amdhsa_next_free_sgpr 100
		.amdhsa_accum_offset 256
		.amdhsa_reserve_vcc 1
		.amdhsa_float_round_mode_32 0
		.amdhsa_float_round_mode_16_64 0
		.amdhsa_float_denorm_mode_32 3
		.amdhsa_float_denorm_mode_16_64 3
		.amdhsa_dx10_clamp 1
		.amdhsa_ieee_mode 1
		.amdhsa_fp16_overflow 0
		.amdhsa_tg_split 0
		.amdhsa_exception_fp_ieee_invalid_op 0
		.amdhsa_exception_fp_denorm_src 0
		.amdhsa_exception_fp_ieee_div_zero 0
		.amdhsa_exception_fp_ieee_overflow 0
		.amdhsa_exception_fp_ieee_underflow 0
		.amdhsa_exception_fp_ieee_inexact 0
		.amdhsa_exception_int_div_zero 0
	.end_amdhsa_kernel

; __global__ void __launch_bounds__(NWAVES * 64, 2) fwd_kernel(Args A) {
amdhsa.kernels:
  - .agpr_count:     0
    .args:
      - .offset:         0
        .size:           160
        .value_kind:     by_value
      - .offset:         160
        .size:           4
        .value_kind:     hidden_block_count_x
      - .offset:         164
        .size:           4
        .value_kind:     hidden_block_count_y
      - .offset:         168
        .size:           4
        .value_kind:     hidden_block_count_z
      - .offset:         172
        .size:           2
        .value_kind:     hidden_group_size_x
      - .offset:         174
        .size:           2
        .value_kind:     hidden_group_size_y
      - .offset:         176
        .size:           2
        .value_kind:     hidden_group_size_z
      - .offset:         178
        .size:           2
        .value_kind:     hidden_remainder_x
      - .offset:         180
        .size:           2
        .value_kind:     hidden_remainder_y
      - .offset:         182
        .size:           2
        .value_kind:     hidden_remainder_z
      - .offset:         200
        .size:           8
        .value_kind:     hidden_global_offset_x
      - .offset:         208
        .size:           8
        .value_kind:     hidden_global_offset_y
      - .offset:         216
        .size:           8
        .value_kind:     hidden_global_offset_z
      - .offset:         224
        .size:           2
        .value_kind:     hidden_grid_dims
      - .offset:         248
        .size:           8
        .value_kind:     hidden_multigrid_sync_arg
      - .offset:         280
        .size:           4
        .value_kind:     hidden_dynamic_lds_size
    .group_segment_fixed_size: 0
    .kernarg_segment_align: 8
    .kernarg_segment_size: 416
    .language:       OpenCL C
    .language_version:
      - 2
      - 0
    .max_flat_workgroup_size: 512
    .name:           _Z10fwd_kernel4Args
    .private_segment_fixed_size: 0
    .sgpr_count:     106
    .sgpr_spill_count: 274
    .symbol:         _Z10fwd_kernel4Args.kd
    .uniform_work_group_size: 1
    .uses_dynamic_stack: false
    .vgpr_count:     254
    .vgpr_spill_count: 0
    .wavefront_size: 64
